# tile decode: division emulation by group size (always 8) replaced by shift/and in the per-unit header (9 GEMM instances), on top of previous
# speedup vs baseline: 1.0229x; 1.0057x over previous
;     __device__ bool next(int i, Unit& u) const {
;         const int ti = i / nseg; u.seg = i - ti * nseg;
;         const long L = (long)ti * G + c; if (L >= nwg) return false;
;         int wgid = (int)L; { const int q = nwg / NXCD, r = nwg % NXCD, xcd = wgid % NXCD, off = wgid / NXCD; wgid = (xcd < r ? xcd * (q + 1) : r * (q + 1) + (xcd - r) * q) + off; }
;         const int nig = WGM * nN, gid = wgid / nig, fm = gid * WGM, gsz = (nM - fm) < WGM ? (nM - fm) : WGM;
;         u.pm = fm + ((wgid % nig) % gsz); u.pn = (wgid % nig) / gsz; return true;
; template <class Epi, bool ALIGN_EPI, bool SP2, class Hook>
; __device__ __forceinline__ void gemm_phase(LAS unsigned char* lds, const Gemm g, const StaticOrder& S, const Epi& E, Acc& acc, const bool fresh, const Hook& H, const int wave_id) {
;     ...
;         const bool has_next = S.next(ui + 1, nxt);
.LBB0_384:
	s_add_i32 s64, s64, 1
	v_readlane_b32 s0, v254, 16
	v_readlane_b32 s2, v249, 2
	s_mul_i32 s0, s64, s0
	s_mul_hi_u32 s1, s64, s2
	s_add_i32 s1, s1, s0
	s_mul_i32 s0, s64, s2
	v_readlane_b32 s2, v253, 19
	v_readlane_b32 s3, v253, 20
	s_add_u32 s2, s0, s2
	v_readlane_b32 s0, v250, 7
	s_addc_u32 s3, s1, s0
	v_cmp_gt_i64_e32 vcc, s[2:3], v[236:237]
	s_mov_b32 s65, s67
	v_cmp_lt_i64_e64 s[0:1], s[2:3], v[234:235]
	s_cbranch_vccnz .LBB0_386
	s_ashr_i32 s3, s2, 31
	s_lshr_b32 s3, s3, 29
	s_add_i32 s3, s2, s3
	s_ashr_i32 s4, s3, 3
	s_and_b32 s3, s3, -8
	s_sub_i32 s2, s2, s3
	s_cmp_lt_i32 s2, 0
	s_movk_i32 s3, 0xb9
	s_cselect_b32 s3, s3, 0xb8
	s_mul_i32 s2, s2, s3
	s_add_i32 s2, s2, s4
	s_mul_hi_i32 s3, s2, 0xb21642c9
	s_add_i32 s3, s3, s2
	s_lshr_b32 s4, s3, 31
	s_ashr_i32 s3, s3, 7
	s_add_i32 s3, s3, s4
	s_lshl_b32 s4, s3, 3
	s_mulk_i32 s3, 0xb8
	s_sub_i32 s2, s2, s3
	s_abs_i32 s3, s2
	s_lshr_b32 s66, s2, 3
	s_and_b32 s2, s2, 7
	s_add_i32 s67, s4, s2

;     __device__ bool next(int i, Unit& u) const {
;     ...
;         int wgid = (int)L; { const int q = nwg / NXCD, r = nwg % NXCD, xcd = wgid % NXCD, off = wgid / NXCD; wgid = (xcd < r ? xcd * (q + 1) : r * (q + 1) + (xcd - r) * q) + off; }
;         const int nig = WGM * nN, gid = wgid / nig, fm = gid * WGM, gsz = (nM - fm) < WGM ? (nM - fm) : WGM;
;         u.pm = fm + ((wgid % nig) % gsz); u.pn = (wgid % nig) / gsz; return true;
.LBB0_696:
	s_ashr_i32 s4, s14, 3
	s_add_i32 s4, s16, s4
	s_ashr_i32 s5, s4, 31
	s_lshr_b32 s5, s5, 28
	s_add_i32 s5, s4, s5
	s_ashr_i32 s14, s5, 4
	s_lshl_b32 s14, s14, 3
	s_and_b32 s5, s5, -16
	s_sub_i32 s4, s4, s5
	s_abs_i32 s5, s4
	s_lshr_b32 s51, s4, 3
	s_and_b32 s4, s4, 7
	s_add_i32 s52, s14, s4

;     __device__ bool next(int i, Unit& u) const {
;     ...
;         int wgid = (int)L; { const int q = nwg / NXCD, r = nwg % NXCD, xcd = wgid % NXCD, off = wgid / NXCD; wgid = (xcd < r ? xcd * (q + 1) : r * (q + 1) + (xcd - r) * q) + off; }
;         const int nig = WGM * nN, gid = wgid / nig, fm = gid * WGM, gsz = (nM - fm) < WGM ? (nM - fm) : WGM;
;         u.pm = fm + ((wgid % nig) % gsz); u.pn = (wgid % nig) / gsz; return true;
.LBB0_773:
	s_ashr_i32 s4, s15, 3
	s_add_i32 s4, s17, s4
	s_ashr_i32 s5, s4, 31
	s_lshr_b32 s5, s5, 27
	s_add_i32 s5, s4, s5
	s_ashr_i32 s15, s5, 5
	s_lshl_b32 s15, s15, 3
	s_andn2_b32 s5, s5, 31
	s_sub_i32 s4, s4, s5
	s_abs_i32 s5, s4
	s_lshr_b32 s57, s4, 3
	s_and_b32 s4, s4, 7
	s_add_i32 s58, s15, s4

;     __device__ bool next(int i, Unit& u) const {
;     ...
;         int wgid = (int)L; { const int q = nwg / NXCD, r = nwg % NXCD, xcd = wgid % NXCD, off = wgid / NXCD; wgid = (xcd < r ? xcd * (q + 1) : r * (q + 1) + (xcd - r) * q) + off; }
;         const int nig = WGM * nN, gid = wgid / nig, fm = gid * WGM, gsz = (nM - fm) < WGM ? (nM - fm) : WGM;
;         u.pm = fm + ((wgid % nig) % gsz); u.pn = (wgid % nig) / gsz; return true;
.LBB0_945:
	s_ashr_i32 s4, s15, 3
	s_add_i32 s4, s17, s4
	s_ashr_i32 s5, s4, 31
	s_lshr_b32 s5, s5, 27
	s_add_i32 s5, s4, s5
	s_ashr_i32 s15, s5, 5
	s_lshl_b32 s15, s15, 3
	s_andn2_b32 s5, s5, 31
	s_sub_i32 s4, s4, s5
	s_abs_i32 s5, s4
	s_lshr_b32 s65, s4, 3
	s_and_b32 s4, s4, 7
	s_add_i32 s66, s15, s4

;     __device__ bool next(int i, Unit& u) const {
;     ...
;         int wgid = (int)L; { const int q = nwg / NXCD, r = nwg % NXCD, xcd = wgid % NXCD, off = wgid / NXCD; wgid = (xcd < r ? xcd * (q + 1) : r * (q + 1) + (xcd - r) * q) + off; }
;         const int nig = WGM * nN, gid = wgid / nig, fm = gid * WGM, gsz = (nM - fm) < WGM ? (nM - fm) : WGM;
;         u.pm = fm + ((wgid % nig) % gsz); u.pn = (wgid % nig) / gsz; return true;
.LBB0_1229:
	s_ashr_i32 s4, s18, 3
	s_add_i32 s4, s20, s4
	s_ashr_i32 s5, s4, 31
	s_lshr_b32 s5, s5, 27
	s_add_i32 s5, s4, s5
	s_ashr_i32 s18, s5, 5
	s_lshl_b32 s18, s18, 3
	s_andn2_b32 s5, s5, 31
	s_sub_i32 s4, s4, s5
	s_abs_i32 s5, s4
	s_lshr_b32 s53, s4, 3
	s_and_b32 s4, s4, 7
	s_add_i32 s54, s18, s4

;     __device__ bool next(int i, Unit& u) const {
;         const int ti = i / nseg; u.seg = i - ti * nseg;
;         const long L = (long)ti * G + c; if (L >= nwg) return false;
;         int wgid = (int)L; { const int q = nwg / NXCD, r = nwg % NXCD, xcd = wgid % NXCD, off = wgid / NXCD; wgid = (xcd < r ? xcd * (q + 1) : r * (q + 1) + (xcd - r) * q) + off; }
;         const int nig = WGM * nN, gid = wgid / nig, fm = gid * WGM, gsz = (nM - fm) < WGM ? (nM - fm) : WGM;
;         u.pm = fm + ((wgid % nig) % gsz); u.pn = (wgid % nig) / gsz; return true;
; template <class Epi, bool ALIGN_EPI, bool SP2, class Hook>
; __device__ __forceinline__ void gemm_phase(LAS unsigned char* lds, const Gemm g, const StaticOrder& S, const Epi& E, Acc& acc, const bool fresh, const Hook& H, const int wave_id) {
;     ...
;         const bool has_next = S.next(ui + 1, nxt);
.LBB0_1454:
	s_add_i32 s30, s30, 1
	v_readlane_b32 s2, v254, 16
	v_readlane_b32 s4, v249, 2
	s_mul_i32 s2, s30, s2
	s_mul_hi_u32 s3, s30, s4
	s_add_i32 s3, s3, s2
	s_mul_i32 s2, s30, s4
	v_readlane_b32 s4, v253, 19
	s_add_u32 s2, s2, s4
	v_readlane_b32 s4, v250, 7
	v_readlane_b32 s5, v253, 20
	s_addc_u32 s3, s3, s4
	v_mov_b64_e32 v[2:3], 0x580
	v_cmp_lt_i64_e64 s[4:5], s[2:3], v[2:3]
	v_mov_b64_e32 v[2:3], 0x57f
	v_cmp_gt_i64_e32 vcc, s[2:3], v[2:3]
	s_mov_b32 s31, s35
	s_cbranch_vccnz .LBB0_1456
	s_ashr_i32 s3, s2, 31
	s_lshr_b32 s3, s3, 29
	s_add_i32 s3, s2, s3
	s_ashr_i32 s6, s3, 3
	s_and_b32 s3, s3, -8
	s_sub_i32 s2, s2, s3
	s_cmp_lt_i32 s2, 0
	s_movk_i32 s3, 0xb1
	s_cselect_b32 s3, s3, 0xb0
	s_mul_i32 s2, s2, s3
	s_add_i32 s2, s2, s6
	s_mul_hi_i32 s3, s2, 0x2e8ba2e9
	s_lshr_b32 s6, s3, 31
	s_ashr_i32 s3, s3, 5
	s_add_i32 s3, s3, s6
	s_lshl_b32 s6, s3, 3
	s_mulk_i32 s3, 0xb0
	s_sub_i32 s2, s2, s3
	s_abs_i32 s3, s2
	s_lshr_b32 s34, s2, 3
	s_and_b32 s2, s2, 7
	s_add_i32 s35, s6, s2

;     __device__ bool next(int i, Unit& u) const {
;     ...
;         int wgid = (int)L; { const int q = nwg / NXCD, r = nwg % NXCD, xcd = wgid % NXCD, off = wgid / NXCD; wgid = (xcd < r ? xcd * (q + 1) : r * (q + 1) + (xcd - r) * q) + off; }
;         const int nig = WGM * nN, gid = wgid / nig, fm = gid * WGM, gsz = (nM - fm) < WGM ? (nM - fm) : WGM;
;         u.pm = fm + ((wgid % nig) % gsz); u.pn = (wgid % nig) / gsz; return true;
.LBB0_1566:
	s_ashr_i32 s4, s10, 3
	s_add_i32 s4, s18, s4
	s_ashr_i32 s5, s4, 31
	s_lshr_b32 s5, s5, 27
	s_add_i32 s5, s4, s5
	s_ashr_i32 s10, s5, 5
	s_lshl_b32 s10, s10, 3
	s_andn2_b32 s5, s5, 31
	s_sub_i32 s4, s4, s5
	s_abs_i32 s5, s4
	s_lshr_b32 s55, s4, 3
	s_and_b32 s4, s4, 7
	s_add_i32 s56, s10, s4

;     __device__ bool next(int i, Unit& u) const {
;     ...
;         int wgid = (int)L; { const int q = nwg / NXCD, r = nwg % NXCD, xcd = wgid % NXCD, off = wgid / NXCD; wgid = (xcd < r ? xcd * (q + 1) : r * (q + 1) + (xcd - r) * q) + off; }
;         const int nig = WGM * nN, gid = wgid / nig, fm = gid * WGM, gsz = (nM - fm) < WGM ? (nM - fm) : WGM;
;         u.pm = fm + ((wgid % nig) % gsz); u.pn = (wgid % nig) / gsz; return true;
.LBB0_1608:
	s_ashr_i32 s4, s14, 3
	s_add_i32 s4, s16, s4
	s_ashr_i32 s5, s4, 31
	s_lshr_b32 s5, s5, 27
	s_add_i32 s5, s4, s5
	s_ashr_i32 s14, s5, 5
	s_lshl_b32 s14, s14, 3
	s_andn2_b32 s5, s5, 31
	s_sub_i32 s4, s4, s5
	s_abs_i32 s5, s4
	s_lshr_b32 s53, s4, 3
	s_and_b32 s4, s4, 7
	s_add_i32 s54, s14, s4
